# thr: third sweep records per key tile up to 64 (query, digit) candidates in a wave-private LDS list; fourth sweep skips tiles whose candidates cannot share the 24-bit prefix
# speedup vs baseline: 1.0028x; 1.0005x over previous
; DI void dsa_thr_item(const Params& p, int b, int qblk, char* smem) {
;     ...
;   for (int pass = 0; pass < 4; ++pass) {
;     for (int i = tid; i < 8192; i += 512) hist[i] = 0u;
;     __syncthreads();
;     const int shift = 24 - 8 * pass;
;     const unsigned mypref = pref[lr];
;     const u16* kib = (const u16*)(p.ws + OFF_KIF) + (size_t)b * 128 * 1024 + lane * 8;
;     bf16x8 kn0, kn1;
;     {
;       const int kt0 = min(wave, qblk);
;       kn0 = ldg8(kib + (size_t)kt0 * 1024); kn1 = ldg8(kib + (size_t)kt0 * 1024 + 512);
;     }
;     for (int kt = wave; kt <= qblk; kt += 8) {
.LBB0_264:
	v_add_u32_e32 v1, 0x200, v1
	s_movk_i32 s0, 0x1dff
	v_cmp_lt_u32_e64 s[0:1], s0, v1
	ds_write_b32 v0, v53
	s_or_b64 s[52:53], s[0:1], s[52:53]
	v_add_u32_e32 v0, 0x800, v0
	s_andn2_b64 exec, exec, s[52:53]
	s_cbranch_execnz .LBB0_264
	s_or_b64 exec, exec, s[52:53]
	s_waitcnt lgkmcnt(0)
	s_barrier
	s_and_saveexec_b64 s[54:55], vcc
	s_cbranch_execz .LBB0_334
	global_load_dwordx4 v[36:39], v[56:57], off offset:1024
	global_load_dwordx4 v[32:35], v[56:57], off
	ds_read_b32 v94, v58 offset:32768
	ds_read_b128 v[184:187], v216 offset:33792
	ds_read_b128 v[188:191], v216 offset:33824
	ds_read_b128 v[192:195], v216 offset:33280
	ds_read_b128 v[196:199], v216 offset:33312
	ds_read_b128 v[200:203], v216 offset:33344
	ds_read_b128 v[220:223], v216 offset:33376
	ds_read_b128 v[224:227], v216 offset:33408
	ds_read_b128 v[228:231], v216 offset:33440
	ds_read_b128 v[232:235], v216 offset:33472
	ds_read_b128 v[236:239], v216 offset:33504
	ds_read_b128 v[240:243], v216 offset:33536
	ds_read_b128 v[244:247], v216 offset:33568
	ds_read_b128 v[248:251], v216 offset:33600
	s_waitcnt lgkmcnt(0)
	s_lshl_b32 s0, s72, 3
	s_sub_i32 s58, 24, s0
	s_mov_b32 s99, -1
	s_cmp_lg_u32 s72, 2
	s_cbranch_scc1 .Lthr_nz2
	v_lshlrev_b32_e32 v0, 10, v167
	v_lshl_add_u32 v0, v0, 2, v0
	v_and_b32_e32 v4, 15, v177
	v_mul_u32_u24_e32 v4, 0x140, v4
	v_mov_b32_e32 v5, 0
	v_add_u32_e32 v0, v0, v4
	v_add_u32_e32 v0, 0x10800, v0
	ds_write_b32 v0, v5
.Lthr_nz2:
	s_mov_b64 s[60:61], 0
	v_mov_b32_e32 v96, v167
	s_branch .LBB0_268

; DI void dsa_thr_item(const Params& p, int b, int qblk, char* smem) {
;     ...
;     for (int kt = wave; kt <= qblk; kt += 8) {
;       const bf16x8 k0 = kn0, k1 = kn1;
;       {
;         const int ktn = min(kt + 8, qblk);
;         kn0 = ldg8(kib + (size_t)ktn * 1024); kn1 = ldg8(kib + (size_t)ktn * 1024 + 512);
;       }
.LBB0_268:
	s_add_i32 s99, s99, 1
	v_mov_b32_e32 v97, v96
	v_add_u32_e32 v96, 8, v97
	v_min_i32_e32 v52, s71, v96
	v_lshlrev_b64 v[0:1], 11, v[52:53]
	s_waitcnt vmcnt(0)
	v_mov_b64_e32 v[42:43], v[38:39]
	s_waitcnt vmcnt(0)
	v_mov_b64_e32 v[46:47], v[34:35]
	v_lshl_add_u64 v[0:1], v[54:55], 0, v[0:1]
	v_mov_b64_e32 v[40:41], v[36:37]
	v_mov_b64_e32 v[44:45], v[32:33]
	global_load_dwordx4 v[32:35], v[0:1], off
	global_load_dwordx4 v[36:39], v[0:1], off offset:1024
	s_cmp_eq_u32 s72, 3
	s_cbranch_scc0 .Lthr_noskip
	v_readfirstlane_b32 s100, v97
	s_cmp_eq_u32 s100, s71
	s_cbranch_scc1 .Lthr_noskip
	s_mul_i32 s100, s99, 0x140
	v_lshlrev_b32_e32 v0, 10, v167
	v_lshl_add_u32 v0, v0, 2, v0
	v_add_u32_e32 v0, 0x10800, v0
	v_add_u32_e32 v0, s100, v0
	v_mov_b32_e32 v6, v177
	v_lshl_add_u32 v1, v6, 2, v0
	ds_read_b32 v2, v0
	ds_read_b32 v3, v1 offset:4
	s_waitcnt lgkmcnt(0)
	v_readfirstlane_b32 s100, v2
	s_cmp_gt_u32 s100, 64
	s_cbranch_scc1 .Lthr_noskip
	v_and_b32_e32 v4, 0x7c, v3
	ds_read_b32 v4, v4 offset:32768
	v_lshrrev_b32_e32 v5, 7, v3
	v_cmp_gt_u32_e64 s[6:7], s100, v6
	s_waitcnt lgkmcnt(0)
	v_and_b32_e32 v4, 0xff, v4
	v_cmp_eq_u32_e64 s[8:9], v4, v5
	s_and_b64 s[6:7], s[6:7], s[8:9]
	s_cmp_lg_u64 s[6:7], 0
	s_cbranch_scc1 .Lthr_noskip
	s_mov_b64 s[0:1], exec
	s_branch .LBB0_267

; DI void dsa_thr_item(const Params& p, int b, int qblk, char* smem) {
;     ...
;       } else {
; #pragma unroll
;         for (int i = 0; i < 16; ++i) {
;           unsigned ky = fkey(sc[i]);
;           unsigned hi = (ky >> shift);
;           if ((hi >> 8) == mypref) atomicAdd(&hist[(hi & 255u) * 32 + lr], 1u);
;         }
.Lthr_h_gen:
	s_add_i32 s62, s58, 8
	s_cmp_eq_u32 s72, 2
	s_cselect_b32 s101, 1, 0
	s_mul_i32 s100, s99, 0x140
	v_lshlrev_b32_e32 v159, 10, v167
	v_lshl_add_u32 v159, v159, 2, v159
	v_add_u32_e32 v159, 0x10800, v159
	v_add_u32_e32 v159, s100, v159
	v_lshrrev_b32_e32 v120, 8, v9
	v_and_b32_e32 v104, 0xff, v9
	v_ashrrev_i32_e32 v105, 31, v22
	v_ashrrev_i32_e32 v106, 31, v21
	v_ashrrev_i32_e32 v107, 31, v20
	v_bitop3_b32 v105, v105, v22, s67 bitop3:0x36
	v_bitop3_b32 v106, v106, v21, s67 bitop3:0x36
	v_bitop3_b32 v107, v107, v20, s67 bitop3:0x36
	v_lshrrev_b32_e32 v121, s62, v105
	v_lshrrev_b32_e32 v122, s62, v106
	v_lshrrev_b32_e32 v123, s62, v107
	v_cmp_eq_u32_e64 s[0:1], v120, v94
	v_cmp_eq_u32_e64 s[6:7], v121, v94
	v_cmp_eq_u32_e64 s[8:9], v122, v94
	v_cmp_eq_u32_e64 s[10:11], v123, v94
	s_or_b64 s[76:77], s[0:1], s[6:7]
	s_or_b64 s[84:85], s[8:9], s[10:11]
	s_or_b64 s[76:77], s[76:77], s[84:85]
	s_cbranch_scc0 .Lthr_g0_skip
	v_bfe_u32 v105, v105, s58, 8
	v_bfe_u32 v106, v106, s58, 8
	v_bfe_u32 v107, v107, s58, 8
	v_lshl_add_u32 v136, v104, 7, v58
	v_lshl_add_u32 v137, v105, 7, v58
	v_lshl_add_u32 v138, v106, 7, v58
	v_lshl_add_u32 v139, v107, 7, v58
	s_and_saveexec_b64 s[74:75], s[0:1]
	s_cbranch_scc0 .Lthr_na_0
	ds_add_u32 v136, v71
	s_cmp_lg_u32 s101, 0
	s_cbranch_scc0 .Lthr_na_0
	ds_add_rtn_u32 v157, v159, v71
	s_waitcnt lgkmcnt(0)
	v_cmp_gt_u32_e64 s[84:85], 64, v157
	v_lshl_add_u32 v158, v157, 2, v159
	s_and_b64 exec, exec, s[84:85]
	ds_write_b32 v158, v136 offset:4
.Lthr_na_0:
	s_mov_b64 exec, s[74:75]
	s_and_saveexec_b64 s[74:75], s[6:7]
	s_cbranch_scc0 .Lthr_na_1
	ds_add_u32 v137, v71
	s_cmp_lg_u32 s101, 0
	s_cbranch_scc0 .Lthr_na_1
	ds_add_rtn_u32 v157, v159, v71
	s_waitcnt lgkmcnt(0)
	v_cmp_gt_u32_e64 s[84:85], 64, v157
	v_lshl_add_u32 v158, v157, 2, v159
	s_and_b64 exec, exec, s[84:85]
	ds_write_b32 v158, v137 offset:4
.Lthr_na_1:
	s_mov_b64 exec, s[74:75]
	s_and_saveexec_b64 s[74:75], s[8:9]
	s_cbranch_scc0 .Lthr_na_2
	ds_add_u32 v138, v71
	s_cmp_lg_u32 s101, 0
	s_cbranch_scc0 .Lthr_na_2
	ds_add_rtn_u32 v157, v159, v71
	s_waitcnt lgkmcnt(0)
	v_cmp_gt_u32_e64 s[84:85], 64, v157
	v_lshl_add_u32 v158, v157, 2, v159
	s_and_b64 exec, exec, s[84:85]
	ds_write_b32 v158, v138 offset:4
.Lthr_na_2:
	s_mov_b64 exec, s[74:75]
	s_and_saveexec_b64 s[74:75], s[10:11]
	s_cbranch_scc0 .Lthr_na_3
	ds_add_u32 v139, v71
	s_cmp_lg_u32 s101, 0
	s_cbranch_scc0 .Lthr_na_3
	ds_add_rtn_u32 v157, v159, v71
	s_waitcnt lgkmcnt(0)
	v_cmp_gt_u32_e64 s[84:85], 64, v157
	v_lshl_add_u32 v158, v157, 2, v159
	s_and_b64 exec, exec, s[84:85]
	ds_write_b32 v158, v139 offset:4
.Lthr_na_3:
	s_mov_b64 exec, s[74:75]
.Lthr_g0_skip:
	v_ashrrev_i32_e32 v108, 31, v19
	v_ashrrev_i32_e32 v109, 31, v18
	v_ashrrev_i32_e32 v110, 31, v17
	v_ashrrev_i32_e32 v111, 31, v16
	v_bitop3_b32 v108, v108, v19, s67 bitop3:0x36
	v_bitop3_b32 v109, v109, v18, s67 bitop3:0x36
	v_bitop3_b32 v110, v110, v17, s67 bitop3:0x36
	v_bitop3_b32 v111, v111, v16, s67 bitop3:0x36
	v_lshrrev_b32_e32 v124, s62, v108
	v_lshrrev_b32_e32 v125, s62, v109
	v_lshrrev_b32_e32 v126, s62, v110
	v_lshrrev_b32_e32 v127, s62, v111
	v_cmp_eq_u32_e64 s[0:1], v124, v94
	v_cmp_eq_u32_e64 s[6:7], v125, v94
	v_cmp_eq_u32_e64 s[8:9], v126, v94
	v_cmp_eq_u32_e64 s[10:11], v127, v94
	s_or_b64 s[76:77], s[0:1], s[6:7]
	s_or_b64 s[84:85], s[8:9], s[10:11]
	s_or_b64 s[76:77], s[76:77], s[84:85]
	s_cbranch_scc0 .Lthr_g1_skip
	v_bfe_u32 v108, v108, s58, 8
	v_bfe_u32 v109, v109, s58, 8
	v_bfe_u32 v110, v110, s58, 8
	v_bfe_u32 v111, v111, s58, 8
	v_lshl_add_u32 v140, v108, 7, v58
	v_lshl_add_u32 v141, v109, 7, v58
	v_lshl_add_u32 v142, v110, 7, v58
	v_lshl_add_u32 v143, v111, 7, v58
	s_and_saveexec_b64 s[74:75], s[0:1]
	s_cbranch_scc0 .Lthr_na_4
	ds_add_u32 v140, v71
	s_cmp_lg_u32 s101, 0
	s_cbranch_scc0 .Lthr_na_4
	ds_add_rtn_u32 v157, v159, v71
	s_waitcnt lgkmcnt(0)
	v_cmp_gt_u32_e64 s[84:85], 64, v157
	v_lshl_add_u32 v158, v157, 2, v159
	s_and_b64 exec, exec, s[84:85]
	ds_write_b32 v158, v140 offset:4
.Lthr_na_4:
	s_mov_b64 exec, s[74:75]
	s_and_saveexec_b64 s[74:75], s[6:7]
	s_cbranch_scc0 .Lthr_na_5
	ds_add_u32 v141, v71
	s_cmp_lg_u32 s101, 0
	s_cbranch_scc0 .Lthr_na_5
	ds_add_rtn_u32 v157, v159, v71
	s_waitcnt lgkmcnt(0)
	v_cmp_gt_u32_e64 s[84:85], 64, v157
	v_lshl_add_u32 v158, v157, 2, v159
	s_and_b64 exec, exec, s[84:85]
	ds_write_b32 v158, v141 offset:4
.Lthr_na_5:
	s_mov_b64 exec, s[74:75]
	s_and_saveexec_b64 s[74:75], s[8:9]
	s_cbranch_scc0 .Lthr_na_6
	ds_add_u32 v142, v71
	s_cmp_lg_u32 s101, 0
	s_cbranch_scc0 .Lthr_na_6
	ds_add_rtn_u32 v157, v159, v71
	s_waitcnt lgkmcnt(0)
	v_cmp_gt_u32_e64 s[84:85], 64, v157
	v_lshl_add_u32 v158, v157, 2, v159
	s_and_b64 exec, exec, s[84:85]
	ds_write_b32 v158, v142 offset:4
.Lthr_na_6:
	s_mov_b64 exec, s[74:75]
	s_and_saveexec_b64 s[74:75], s[10:11]
	s_cbranch_scc0 .Lthr_na_7
	ds_add_u32 v143, v71
	s_cmp_lg_u32 s101, 0
	s_cbranch_scc0 .Lthr_na_7
	ds_add_rtn_u32 v157, v159, v71
	s_waitcnt lgkmcnt(0)
	v_cmp_gt_u32_e64 s[84:85], 64, v157
	v_lshl_add_u32 v158, v157, 2, v159
	s_and_b64 exec, exec, s[84:85]
	ds_write_b32 v158, v143 offset:4

; DI void dsa_thr_item(const Params& p, int b, int qblk, char* smem) {
;     ...
;       } else {
; #pragma unroll
;         for (int i = 0; i < 16; ++i) {
;           unsigned ky = fkey(sc[i]);
;           unsigned hi = (ky >> shift);
;           if ((hi >> 8) == mypref) atomicAdd(&hist[(hi & 255u) * 32 + lr], 1u);
;         }
.Lthr_g1_skip:
	v_ashrrev_i32_e32 v112, 31, v7
	v_ashrrev_i32_e32 v113, 31, v6
	v_ashrrev_i32_e32 v114, 31, v5
	v_ashrrev_i32_e32 v115, 31, v4
	v_bitop3_b32 v112, v112, v7, s67 bitop3:0x36
	v_bitop3_b32 v113, v113, v6, s67 bitop3:0x36
	v_bitop3_b32 v114, v114, v5, s67 bitop3:0x36
	v_bitop3_b32 v115, v115, v4, s67 bitop3:0x36
	v_lshrrev_b32_e32 v128, s62, v112
	v_lshrrev_b32_e32 v129, s62, v113
	v_lshrrev_b32_e32 v130, s62, v114
	v_lshrrev_b32_e32 v131, s62, v115
	v_cmp_eq_u32_e64 s[0:1], v128, v94
	v_cmp_eq_u32_e64 s[6:7], v129, v94
	v_cmp_eq_u32_e64 s[8:9], v130, v94
	v_cmp_eq_u32_e64 s[10:11], v131, v94
	s_or_b64 s[76:77], s[0:1], s[6:7]
	s_or_b64 s[84:85], s[8:9], s[10:11]
	s_or_b64 s[76:77], s[76:77], s[84:85]
	s_cbranch_scc0 .Lthr_g2_skip
	v_bfe_u32 v112, v112, s58, 8
	v_bfe_u32 v113, v113, s58, 8
	v_bfe_u32 v114, v114, s58, 8
	v_bfe_u32 v115, v115, s58, 8
	v_lshl_add_u32 v144, v112, 7, v58
	v_lshl_add_u32 v145, v113, 7, v58
	v_lshl_add_u32 v146, v114, 7, v58
	v_lshl_add_u32 v147, v115, 7, v58
	s_and_saveexec_b64 s[74:75], s[0:1]
	s_cbranch_scc0 .Lthr_na_8
	ds_add_u32 v144, v71
	s_cmp_lg_u32 s101, 0
	s_cbranch_scc0 .Lthr_na_8
	ds_add_rtn_u32 v157, v159, v71
	s_waitcnt lgkmcnt(0)
	v_cmp_gt_u32_e64 s[84:85], 64, v157
	v_lshl_add_u32 v158, v157, 2, v159
	s_and_b64 exec, exec, s[84:85]
	ds_write_b32 v158, v144 offset:4
.Lthr_na_8:
	s_mov_b64 exec, s[74:75]
	s_and_saveexec_b64 s[74:75], s[6:7]
	s_cbranch_scc0 .Lthr_na_9
	ds_add_u32 v145, v71
	s_cmp_lg_u32 s101, 0
	s_cbranch_scc0 .Lthr_na_9
	ds_add_rtn_u32 v157, v159, v71
	s_waitcnt lgkmcnt(0)
	v_cmp_gt_u32_e64 s[84:85], 64, v157
	v_lshl_add_u32 v158, v157, 2, v159
	s_and_b64 exec, exec, s[84:85]
	ds_write_b32 v158, v145 offset:4
.Lthr_na_9:
	s_mov_b64 exec, s[74:75]
	s_and_saveexec_b64 s[74:75], s[8:9]
	s_cbranch_scc0 .Lthr_na_10
	ds_add_u32 v146, v71
	s_cmp_lg_u32 s101, 0
	s_cbranch_scc0 .Lthr_na_10
	ds_add_rtn_u32 v157, v159, v71
	s_waitcnt lgkmcnt(0)
	v_cmp_gt_u32_e64 s[84:85], 64, v157
	v_lshl_add_u32 v158, v157, 2, v159
	s_and_b64 exec, exec, s[84:85]
	ds_write_b32 v158, v146 offset:4
.Lthr_na_10:
	s_mov_b64 exec, s[74:75]
	s_and_saveexec_b64 s[74:75], s[10:11]
	s_cbranch_scc0 .Lthr_na_11
	ds_add_u32 v147, v71
	s_cmp_lg_u32 s101, 0
	s_cbranch_scc0 .Lthr_na_11
	ds_add_rtn_u32 v157, v159, v71
	s_waitcnt lgkmcnt(0)
	v_cmp_gt_u32_e64 s[84:85], 64, v157
	v_lshl_add_u32 v158, v157, 2, v159
	s_and_b64 exec, exec, s[84:85]
	ds_write_b32 v158, v147 offset:4

; DI void dsa_thr_item(const Params& p, int b, int qblk, char* smem) {
;     ...
;       } else {
; #pragma unroll
;         for (int i = 0; i < 16; ++i) {
;           unsigned ky = fkey(sc[i]);
;           unsigned hi = (ky >> shift);
;           if ((hi >> 8) == mypref) atomicAdd(&hist[(hi & 255u) * 32 + lr], 1u);
;         }
.Lthr_g2_skip:
	v_ashrrev_i32_e32 v116, 31, v3
	v_ashrrev_i32_e32 v117, 31, v2
	v_ashrrev_i32_e32 v118, 31, v1
	v_ashrrev_i32_e32 v119, 31, v0
	v_bitop3_b32 v116, v116, v3, s67 bitop3:0x36
	v_bitop3_b32 v117, v117, v2, s67 bitop3:0x36
	v_bitop3_b32 v118, v118, v1, s67 bitop3:0x36
	v_bitop3_b32 v119, v119, v0, s67 bitop3:0x36
	v_lshrrev_b32_e32 v132, s62, v116
	v_lshrrev_b32_e32 v133, s62, v117
	v_lshrrev_b32_e32 v134, s62, v118
	v_lshrrev_b32_e32 v135, s62, v119
	v_cmp_eq_u32_e64 s[0:1], v132, v94
	v_cmp_eq_u32_e64 s[6:7], v133, v94
	v_cmp_eq_u32_e64 s[8:9], v134, v94
	v_cmp_eq_u32_e64 s[10:11], v135, v94
	s_or_b64 s[76:77], s[0:1], s[6:7]
	s_or_b64 s[84:85], s[8:9], s[10:11]
	s_or_b64 s[76:77], s[76:77], s[84:85]
	s_cbranch_scc0 .Lthr_g3_skip
	v_bfe_u32 v116, v116, s58, 8
	v_bfe_u32 v117, v117, s58, 8
	v_bfe_u32 v118, v118, s58, 8
	v_bfe_u32 v119, v119, s58, 8
	v_lshl_add_u32 v148, v116, 7, v58
	v_lshl_add_u32 v149, v117, 7, v58
	v_lshl_add_u32 v150, v118, 7, v58
	v_lshl_add_u32 v151, v119, 7, v58
	s_and_saveexec_b64 s[74:75], s[0:1]
	s_cbranch_scc0 .Lthr_na_12
	ds_add_u32 v148, v71
	s_cmp_lg_u32 s101, 0
	s_cbranch_scc0 .Lthr_na_12
	ds_add_rtn_u32 v157, v159, v71
	s_waitcnt lgkmcnt(0)
	v_cmp_gt_u32_e64 s[84:85], 64, v157
	v_lshl_add_u32 v158, v157, 2, v159
	s_and_b64 exec, exec, s[84:85]
	ds_write_b32 v158, v148 offset:4
.Lthr_na_12:
	s_mov_b64 exec, s[74:75]
	s_and_saveexec_b64 s[74:75], s[6:7]
	s_cbranch_scc0 .Lthr_na_13
	ds_add_u32 v149, v71
	s_cmp_lg_u32 s101, 0
	s_cbranch_scc0 .Lthr_na_13
	ds_add_rtn_u32 v157, v159, v71
	s_waitcnt lgkmcnt(0)
	v_cmp_gt_u32_e64 s[84:85], 64, v157
	v_lshl_add_u32 v158, v157, 2, v159
	s_and_b64 exec, exec, s[84:85]
	ds_write_b32 v158, v149 offset:4
.Lthr_na_13:
	s_mov_b64 exec, s[74:75]
	s_and_saveexec_b64 s[74:75], s[8:9]
	s_cbranch_scc0 .Lthr_na_14
	ds_add_u32 v150, v71
	s_cmp_lg_u32 s101, 0
	s_cbranch_scc0 .Lthr_na_14
	ds_add_rtn_u32 v157, v159, v71
	s_waitcnt lgkmcnt(0)
	v_cmp_gt_u32_e64 s[84:85], 64, v157
	v_lshl_add_u32 v158, v157, 2, v159
	s_and_b64 exec, exec, s[84:85]
	ds_write_b32 v158, v150 offset:4
.Lthr_na_14:
	s_mov_b64 exec, s[74:75]
	s_and_saveexec_b64 s[74:75], s[10:11]
	s_cbranch_scc0 .Lthr_na_15
	ds_add_u32 v151, v71
	s_cmp_lg_u32 s101, 0
	s_cbranch_scc0 .Lthr_na_15
	ds_add_rtn_u32 v157, v159, v71
	s_waitcnt lgkmcnt(0)
	v_cmp_gt_u32_e64 s[84:85], 64, v157
	v_lshl_add_u32 v158, v157, 2, v159
	s_and_b64 exec, exec, s[84:85]
	ds_write_b32 v158, v151 offset:4
